# HGRN2 scan: fcanonicalize folded into the -100 clamp in gate waves (54 v_max removed) + seg-only operand v_mov copies moved to the !seg side in MFMA waves
# speedup vs baseline: 1.0027x; 1.0027x over previous
; #define LAS __attribute__((address_space(3)))
; #define MFMA32(a, b, c) __builtin_amdgcn_mfma_f32_32x32x16_bf16((a), (b), (c), 0, 0, 0)
; DI void hgrn_item(int item, const float* lbl, const bf16* U1, const bf16* UC1, const bf16* VT, const bf16* VTC, bf16* OF, bf16* OB, LAS unsigned char* lds) {
;     ...
;                 const LAS bf16* kp_ = Kt + l32 * HP + 8 * hi; const LAS bf16* ap_ = Qp + l32 * HP + 8 * hi;     const LAS bf16* qp_ = Qp + l32 * HP + 4 * hi; const LAS bf16* tp_ = KtT + l32 * HKP + 4 * hi;
;     ...
;                 f32x16 pT, o;
; #pragma unroll
;                 for (int i = 0; i < 16; ++i) { pT[i] = 0.f; o[i] = 0.f; }
;                 bf16x8 kA = vf0, aA = vf0, qA = vf0, tA = vf0, kB = vf0, aB = vf0, qB = vf0, tB = vf0;
;                 HG_RD(0, kA, aA, qA, tA);
; #pragma unroll
;                 for (int kt = 0; kt < 4; ++kt) {
;                     bf16x8 so0 = vf0, so1 = vf0;
;                     if (seg) { so0 = pack8(S[kt], 0); so1 = pack8(S[kt], 1); }
;                     HG_RD(2 * kt + 1, kB, aB, qB, tB);
;                     if (seg) { pT = MFMA32(kA, aA, pT); o = MFMA32(qA, so0, o); }
;                     S[kt] = MFMA32(tA, vf0, S[kt]);
;                     if (kt < 3) HG_RD(2 * kt + 2, kA, aA, qA, tA);
.LBB0_422:
	s_bitcmp1_b32 s62, 0
	s_cselect_b32 s0, 0, 0x9000
	s_add_i32 s0, s0, 0
	v_add3_u32 v166, s0, v189, v196
	v_add_u32_e32 v70, 0x6000, v166
	ds_read2_b64 v[138:141], v70 offset0:192 offset1:194
	v_lshlrev_b32_e32 v66, 1, v187
	v_add3_u32 v197, s0, v205, v66
	v_cndmask_b32_e64 v66, 0, 1, s[70:71]
	v_cmp_ne_u32_e64 s[58:59], 1, v66
	v_add_u32_e32 v66, v197, v207
	s_andn2_b64 vcc, exec, s[70:71]
	v_add_u32_e32 v247, 0x2000, v66
	s_cbranch_vccnz .Lscan_e1
	ds_read_b128 v[114:117], v197 offset:17408
	ds_read_b128 v[118:121], v197 offset:8704
	ds_read2_b64 v[122:125], v247 offset0:64 offset1:66
.LBB0_424:
	s_and_b64 vcc, exec, s[70:71]
	s_cbranch_vccz .Lscan_e2
	v_cvt_pk_bf16_f32 v66, v50, v51
	v_cvt_pk_bf16_f32 v67, v52, v53
	v_cvt_pk_bf16_f32 v68, v54, v55
	v_cvt_pk_bf16_f32 v69, v56, v57
	v_cvt_pk_bf16_f32 v142, v58, v59
	v_cvt_pk_bf16_f32 v143, v60, v61
	v_cvt_pk_bf16_f32 v144, v62, v63
	v_cvt_pk_bf16_f32 v145, v96, v97
.LBB0_426:
	ds_read2_b64 v[146:149], v70 offset0:196 offset1:198
	s_and_b64 vcc, exec, s[58:59]
	s_cbranch_vccnz .Lscan_e3
	ds_read_b128 v[126:129], v197 offset:17440
	ds_read_b128 v[130:133], v197 offset:8736
	ds_read2_b64 v[134:137], v247 offset0:68 offset1:70

; #define MFMA32(a, b, c) __builtin_amdgcn_mfma_f32_32x32x16_bf16((a), (b), (c), 0, 0, 0)
; DI void hgrn_item(int item, const float* lbl, const bf16* U1, const bf16* UC1, const bf16* VT, const bf16* VTC, bf16* OF, bf16* OB, LAS unsigned char* lds) {
;     ...
;                 for (int kt = 0; kt < 4; ++kt) {
;                     bf16x8 so0 = vf0, so1 = vf0;
;                     if (seg) { so0 = pack8(S[kt], 0); so1 = pack8(S[kt], 1); }
;                     HG_RD(2 * kt + 1, kB, aB, qB, tB);
;                     if (seg) { pT = MFMA32(kA, aA, pT); o = MFMA32(qA, so0, o); }
;                     S[kt] = MFMA32(tA, vf0, S[kt]);
;                     if (kt < 3) HG_RD(2 * kt + 2, kA, aA, qA, tA);
;                     if (seg) { pT = MFMA32(kB, aB, pT); o = MFMA32(qB, so1, o); }
;                     S[kt] = MFMA32(tB, vf1, S[kt]);
.LBB0_435:
	s_waitcnt lgkmcnt(1)
	v_mfma_f32_32x32x16_bf16 v[50:65], v[146:149], v[106:109], v[50:65]
	s_and_b64 vcc, exec, s[58:59]
	s_cbranch_vccnz .LBB0_461
	v_cvt_pk_bf16_f32 v146, v34, v35
	v_cvt_pk_bf16_f32 v147, v36, v37
	v_cvt_pk_bf16_f32 v148, v38, v39
	v_cvt_pk_bf16_f32 v149, v40, v41
	v_cvt_pk_bf16_f32 v142, v42, v43
	v_cvt_pk_bf16_f32 v143, v44, v45
	v_cvt_pk_bf16_f32 v144, v46, v47
	v_cvt_pk_bf16_f32 v145, v154, v155
	ds_read2_b64 v[158:161], v150 offset0:4 offset1:6
	s_and_b64 vcc, exec, s[58:59]
	s_cbranch_vccz .LBB0_462

; #define LAS __attribute__((address_space(3)))
; #define MFMA32(a, b, c) __builtin_amdgcn_mfma_f32_32x32x16_bf16((a), (b), (c), 0, 0, 0)
; DI void hgrn_item(int item, const float* lbl, const bf16* U1, const bf16* UC1, const bf16* VT, const bf16* VTC, bf16* OF, bf16* OB, LAS unsigned char* lds) {
;     ...
;                     HG_RD(2 * kt + 1, kB, aB, qB, tB);
;                     if (seg) { pT = MFMA32(kA, aA, pT); o = MFMA32(qA, so0, o); }
;                     S[kt] = MFMA32(tA, vf0, S[kt]);
;                     if (kt < 3) HG_RD(2 * kt + 2, kA, aA, qA, tA);
;                     if (seg) { pT = MFMA32(kB, aB, pT); o = MFMA32(qB, so1, o); }
;                     S[kt] = MFMA32(tB, vf1, S[kt]);
;                     if (kt > 0) {
; #pragma unroll
;                         for (int gq = 0; gq < 4; ++gq) { const f32x4 d4 = *(const LAS f32x4*)(dv + 32 * (kt - 1) + 8 * gq + 4 * hi);
;                             S[kt - 1][4 * gq] *= d4.x; S[kt - 1][4 * gq + 1] *= d4.y; S[kt - 1][4 * gq + 2] *= d4.z; S[kt - 1][4 * gq + 3] *= d4.w; } }
.LBB0_443:
	v_lshl_add_u32 v248, v190, 2, s0
	s_waitcnt lgkmcnt(1)
	v_mfma_f32_32x32x16_bf16 v[34:49], v[158:161], v[106:109], v[34:49]
	ds_read_b128 v[150:153], v248 offset:36352
	ds_read_b128 v[146:149], v248 offset:36384
	ds_read_b128 v[142:145], v248 offset:36416
	ds_read_b128 v[138:141], v248 offset:36448
	s_and_b64 vcc, exec, s[58:59]
	s_cbranch_vccnz .LBB0_463
	v_cvt_pk_bf16_f32 v162, v18, v19
	v_cvt_pk_bf16_f32 v163, v20, v21
	v_cvt_pk_bf16_f32 v164, v22, v23
	v_cvt_pk_bf16_f32 v165, v24, v25
	v_cvt_pk_bf16_f32 v158, v26, v27
	v_cvt_pk_bf16_f32 v159, v28, v29
	v_cvt_pk_bf16_f32 v160, v30, v31
	v_cvt_pk_bf16_f32 v161, v170, v171
	ds_read2_b64 v[174:177], v167 offset0:68 offset1:70
	s_and_b64 vcc, exec, s[58:59]
	s_cbranch_vccz .LBB0_464

; #define LAS __attribute__((address_space(3)))
; #define MFMA32(a, b, c) __builtin_amdgcn_mfma_f32_32x32x16_bf16((a), (b), (c), 0, 0, 0)
; DI void hgrn_item(int item, const float* lbl, const bf16* U1, const bf16* UC1, const bf16* VT, const bf16* VTC, bf16* OF, bf16* OB, LAS unsigned char* lds) {
;     ...
;                     HG_RD(2 * kt + 1, kB, aB, qB, tB);
;                     if (seg) { pT = MFMA32(kA, aA, pT); o = MFMA32(qA, so0, o); }
;                     S[kt] = MFMA32(tA, vf0, S[kt]);
;                     if (kt < 3) HG_RD(2 * kt + 2, kA, aA, qA, tA);
;                     if (seg) { pT = MFMA32(kB, aB, pT); o = MFMA32(qB, so1, o); }
;                     S[kt] = MFMA32(tB, vf1, S[kt]);
;                     if (kt > 0) {
; #pragma unroll
;                         for (int gq = 0; gq < 4; ++gq) { const f32x4 d4 = *(const LAS f32x4*)(dv + 32 * (kt - 1) + 8 * gq + 4 * hi);
;                             S[kt - 1][4 * gq] *= d4.x; S[kt - 1][4 * gq + 1] *= d4.y; S[kt - 1][4 * gq + 2] *= d4.z; S[kt - 1][4 * gq + 3] *= d4.w; } }
.LBB0_451:
	s_waitcnt lgkmcnt(1)
	v_mfma_f32_32x32x16_bf16 v[18:33], v[174:177], v[106:109], v[18:33]
	ds_read_b128 v[166:169], v248 offset:36480
	ds_read_b128 v[162:165], v248 offset:36512
	ds_read_b128 v[158:161], v248 offset:36544
	ds_read_b128 v[154:157], v248 offset:36576
	s_and_b64 vcc, exec, s[58:59]
	s_cbranch_vccnz .LBB0_465
	v_cvt_pk_bf16_f32 v182, v2, v3
	v_cvt_pk_bf16_f32 v183, v4, v5
	v_cvt_pk_bf16_f32 v184, v6, v7
	v_cvt_pk_bf16_f32 v185, v8, v9
	v_cvt_pk_bf16_f32 v174, v10, v11
	v_cvt_pk_bf16_f32 v175, v12, v13
	v_cvt_pk_bf16_f32 v176, v14, v15
	v_cvt_pk_bf16_f32 v177, v178, v179
	ds_read2_b64 v[178:181], v180 offset0:132 offset1:134
	s_and_b64 vcc, exec, s[58:59]
	s_cbranch_vccz .LBB0_466

; DI void hgrn_item(int item, const float* lbl, const bf16* U1, const bf16* UC1, const bf16* VT, const bf16* VTC, bf16* OF, bf16* OB, LAS unsigned char* lds) {
;     ...
;                     bf16x8 so0 = vf0, so1 = vf0;
;                     if (seg) { so0 = pack8(S[kt], 0); so1 = pack8(S[kt], 1); }
;                     HG_RD(2 * kt + 1, kB, aB, qB, tB);
.LBB0_461:
	v_mov_b64_e32 v[148:149], v[112:113]
	v_mov_b64_e32 v[144:145], v[112:113]
	v_mov_b64_e32 v[146:147], v[110:111]
	v_mov_b64_e32 v[142:143], v[110:111]
	ds_read2_b64 v[158:161], v150 offset0:4 offset1:6
	s_and_b64 vcc, exec, s[58:59]
	s_cbranch_vccnz .LBB0_437

; DI void hgrn_item(int item, const float* lbl, const bf16* U1, const bf16* UC1, const bf16* VT, const bf16* VTC, bf16* OF, bf16* OB, LAS unsigned char* lds) {
;     ...
;                     bf16x8 so0 = vf0, so1 = vf0;
;                     if (seg) { so0 = pack8(S[kt], 0); so1 = pack8(S[kt], 1); }
;                     HG_RD(2 * kt + 1, kB, aB, qB, tB);
.LBB0_463:
	v_mov_b64_e32 v[164:165], v[112:113]
	v_mov_b64_e32 v[160:161], v[112:113]
	v_mov_b64_e32 v[162:163], v[110:111]
	v_mov_b64_e32 v[158:159], v[110:111]
	ds_read2_b64 v[174:177], v167 offset0:68 offset1:70
	s_and_b64 vcc, exec, s[58:59]
	s_cbranch_vccnz .LBB0_445

; DI void hgrn_item(int item, const float* lbl, const bf16* U1, const bf16* UC1, const bf16* VT, const bf16* VTC, bf16* OF, bf16* OB, LAS unsigned char* lds) {
;     ...
;                     bf16x8 so0 = vf0, so1 = vf0;
;                     if (seg) { so0 = pack8(S[kt], 0); so1 = pack8(S[kt], 1); }
;                     HG_RD(2 * kt + 1, kB, aB, qB, tB);
.LBB0_465:
	v_mov_b64_e32 v[184:185], v[112:113]
	v_mov_b64_e32 v[176:177], v[112:113]
	v_mov_b64_e32 v[182:183], v[110:111]
	v_mov_b64_e32 v[174:175], v[110:111]
	ds_read2_b64 v[178:181], v180 offset0:132 offset1:134
	s_and_b64 vcc, exec, s[58:59]
	s_cbranch_vccnz .LBB0_453

; DI void hgrn_item(int item, const float* lbl, const bf16* U1, const bf16* UC1, const bf16* VT, const bf16* VTC, bf16* OF, bf16* OB, LAS unsigned char* lds) {
;     ...
;                 bf16x8 kA = vf0, aA = vf0, qA = vf0, tA = vf0, kB = vf0, aB = vf0, qB = vf0, tB = vf0;
;                 HG_RD(0, kA, aA, qA, tA);
; #pragma unroll
;                 for (int kt = 0; kt < 4; ++kt) {
;                     bf16x8 so0 = vf0, so1 = vf0;
;                     if (seg) { so0 = pack8(S[kt], 0); so1 = pack8(S[kt], 1); }
;                     HG_RD(2 * kt + 1, kB, aB, qB, tB);
.Lscan_e1:
	v_mov_b64_e32 v[116:117], v[112:113]
	v_mov_b64_e32 v[120:121], v[112:113]
	v_mov_b64_e32 v[114:115], v[110:111]
	v_mov_b64_e32 v[118:119], v[110:111]
	v_mov_b32_e32 v122, v110
	v_mov_b32_e32 v123, v111
	v_mov_b32_e32 v124, v112
	v_mov_b32_e32 v125, v113
	s_branch .LBB0_424
.Lscan_e2:
	v_mov_b64_e32 v[66:67], v[110:111]
	v_mov_b64_e32 v[144:145], v[112:113]
	v_mov_b64_e32 v[68:69], v[112:113]
	v_mov_b64_e32 v[142:143], v[110:111]
	s_branch .LBB0_426
.Lscan_e3:
	v_mov_b64_e32 v[128:129], v[112:113]
	v_mov_b64_e32 v[132:133], v[112:113]
	v_mov_b64_e32 v[126:127], v[110:111]
	v_mov_b64_e32 v[130:131], v[110:111]
	v_mov_b32_e32 v134, v110
	v_mov_b32_e32 v135, v111
	v_mov_b32_e32 v136, v112
	v_mov_b32_e32 v137, v113
	s_branch .LBB0_428

; __device__ __forceinline__ float bflo(unsigned u) { return __uint_as_float(u << 16); }
; __device__ __forceinline__ float bfhi(unsigned u) { return __uint_as_float(u & 0xffff0000u); }
; #define LAS __attribute__((address_space(3)))
; DI unsigned pk2(float lo, float hi) { f32x2_t v = {lo, hi}; bf16x2_t b = __builtin_convertvector(v, bf16x2_t); return __builtin_bit_cast(unsigned, b); }
; template <int NC> DI void hg_gate_tick(const HgGate& c, int t, const unsigned (&xo_c)[8], const unsigned (&q_c)[8], const unsigned (&xo_n)[8], unsigned (&xo_p)[8], unsigned (&q_p)[8]) {
;     ...
;         const float d0 = __builtin_amdgcn_exp2f(tot0), d1 = __builtin_amdgcn_exp2f(tot1);
;         float k0v[8], k1v[8], r0[8], r1[8];
;         const float ri0 = __builtin_amdgcn_rcpf(__builtin_amdgcn_exp2f(fmaxf(of0, -100.f))), ri1 = __builtin_amdgcn_rcpf(__builtin_amdgcn_exp2f(fmaxf(of1, -100.f)));
; #pragma unroll
;         for (int i = 0; i < 8; ++i) { const int j = 8 * tqs + i;
;             const float e0 = __builtin_amdgcn_exp2f(fmaxf(c0[i], -100.f)), e1 = __builtin_amdgcn_exp2f(fmaxf(c1[i], -100.f));
;             r0[i] = __builtin_amdgcn_rcpf(e0); r1[i] = __builtin_amdgcn_rcpf(e1);
;             if (seg) Qp[j * (HP / 2) + kp] = pk2(pg8::bflo(q_c[i]) * e0, pg8::bfhi(q_c[i]) * e1); }
; #pragma unroll
;         for (int i = 0; i < 8; ++i) { const int j = 8 * tqs + i;
;             const float p0 = dir ? (i < 7 ? r0[i < 7 ? i + 1 : 7] : ri0) : (i > 0 ? r0[i > 0 ? i - 1 : 0] : ri0), p1 = dir ? (i < 7 ? r1[i < 7 ? i + 1 : 7] : ri1) : (i > 0 ? r1[i > 0 ? i - 1 : 0] : ri1);
;             k0v[i] = r0[i] - p0; k1v[i] = r1[i] - p1;
;             Kt[j * (HP / 2) + kp] = pk2(k0v[i], k1v[i]); }
;         { u32x4 w; w.x = pk2(k0v[0], k0v[1]); w.y = pk2(k0v[2], k0v[3]); w.z = pk2(k0v[4], k0v[5]); w.w = pk2(k0v[6], k0v[7]); *(LAS u32x4*)(KtT + (2 * kp) * HKP + 8 * tqs) = w; }
;         { u32x4 w; w.x = pk2(k1v[0], k1v[1]); w.y = pk2(k1v[2], k1v[3]); w.z = pk2(k1v[4], k1v[5]); w.w = pk2(k1v[6], k1v[7]); *(LAS u32x4*)(KtT + (2 * kp + 1) * HKP + 8 * tqs) = w; }
.LBB0_472:
	v_max_f32_e32 v28, 0xc2c80000, v77
	v_max_f32_e32 v29, 0xc2c80000, v90
	v_exp_f32_e32 v28, v28
	v_exp_f32_e32 v29, v29
	v_rcp_f32_e32 v14, v14
	v_rcp_f32_e32 v15, v15
	v_rcp_f32_e32 v28, v28
	v_rcp_f32_e32 v29, v29
	v_rcp_f32_e32 v16, v16
	v_rcp_f32_e32 v17, v17
	v_rcp_f32_e32 v12, v12
	v_rcp_f32_e32 v13, v13
	v_rcp_f32_e32 v18, v18
	v_cndmask_b32_e64 v30, v14, v28, s[22:23]
	v_cndmask_b32_e64 v31, v15, v29, s[22:23]
	v_rcp_f32_e32 v20, v20
	v_rcp_f32_e32 v21, v21
	v_rcp_f32_e32 v19, v19
	v_sub_f32_e32 v30, v12, v30
	v_sub_f32_e32 v31, v13, v31
	v_cndmask_b32_e64 v12, v16, v12, s[22:23]
	v_cndmask_b32_e64 v13, v17, v13, s[22:23]
	v_sub_f32_e32 v12, v14, v12
	v_sub_f32_e32 v33, v15, v13
	v_cvt_pk_bf16_f32 v32, v30, v31
	v_cvt_pk_bf16_f32 v13, v12, v33
	v_rcp_f32_e32 v22, v22
	ds_write2_b32 v78, v32, v13 offset1:68
	v_cndmask_b32_e64 v13, v18, v14, s[22:23]
	v_rcp_f32_e32 v24, v24
	v_rcp_f32_e32 v25, v25
	v_rcp_f32_e32 v23, v23
	v_cndmask_b32_e64 v14, v19, v15, s[22:23]
	v_sub_f32_e32 v13, v16, v13
	v_cndmask_b32_e64 v15, v20, v16, s[22:23]
	v_cndmask_b32_e64 v16, v21, v17, s[22:23]
	v_sub_f32_e32 v32, v17, v14
	v_sub_f32_e32 v15, v18, v15
	v_sub_f32_e32 v16, v19, v16
	v_cvt_pk_bf16_f32 v14, v13, v32
	v_cvt_pk_bf16_f32 v17, v15, v16
	v_rcp_f32_e32 v26, v26
	v_rcp_f32_e32 v27, v27
	ds_write2_b32 v78, v14, v17 offset0:136 offset1:204
	v_cndmask_b32_e64 v14, v22, v18, s[22:23]
	v_cndmask_b32_e64 v17, v23, v19, s[22:23]
	v_sub_f32_e32 v14, v20, v14
	v_cndmask_b32_e64 v19, v24, v20, s[22:23]
	v_cndmask_b32_e64 v20, v25, v21, s[22:23]
	v_sub_f32_e32 v17, v21, v17
	v_sub_f32_e32 v19, v22, v19
	v_sub_f32_e32 v20, v23, v20
	v_cvt_pk_bf16_f32 v18, v14, v17
	v_cvt_pk_bf16_f32 v21, v19, v20
	ds_write2_b32 v79, v18, v21 offset0:16 offset1:84
	v_cndmask_b32_e64 v18, v26, v22, s[22:23]
	v_cndmask_b32_e64 v21, v27, v23, s[22:23]
	v_cndmask_b32_e64 v23, v28, v24, s[22:23]
	v_sub_f32_e32 v18, v24, v18
	v_cndmask_b32_e64 v24, v29, v25, s[22:23]
	v_sub_f32_e32 v23, v26, v23
	v_sub_f32_e32 v21, v25, v21
	v_sub_f32_e32 v24, v27, v24
	v_cvt_pk_bf16_f32 v12, v30, v12
	v_cvt_pk_bf16_f32 v13, v13, v15
	v_cvt_pk_bf16_f32 v14, v14, v19
	v_cvt_pk_bf16_f32 v15, v18, v23
	v_cvt_pk_bf16_f32 v22, v18, v21
	v_cvt_pk_bf16_f32 v25, v23, v24
	ds_write_b128 v80, v[12:15] offset:26112
	v_cvt_pk_bf16_f32 v12, v31, v33
	v_cvt_pk_bf16_f32 v13, v32, v16
	v_cvt_pk_bf16_f32 v14, v17, v20
	v_cvt_pk_bf16_f32 v15, v21, v24
	s_and_b64 vcc, exec, s[36:37]
	ds_write2_b32 v79, v22, v25 offset0:152 offset1:220
	ds_write_b128 v81, v[12:15] offset:26112
	s_cbranch_vccz .LBB0_572

; __device__ __forceinline__ float bflo(unsigned u) { return __uint_as_float(u << 16); }
; __device__ __forceinline__ float bfhi(unsigned u) { return __uint_as_float(u & 0xffff0000u); }
; #define LAS __attribute__((address_space(3)))
; DI unsigned pk2(float lo, float hi) { f32x2_t v = {lo, hi}; bf16x2_t b = __builtin_convertvector(v, bf16x2_t); return __builtin_bit_cast(unsigned, b); }
; template <int NC> DI void hg_gate_tick(const HgGate& c, int t, const unsigned (&xo_c)[8], const unsigned (&q_c)[8], const unsigned (&xo_n)[8], unsigned (&xo_p)[8], unsigned (&q_p)[8]) {
;     ...
;         const float d0 = __builtin_amdgcn_exp2f(tot0), d1 = __builtin_amdgcn_exp2f(tot1);
;         float k0v[8], k1v[8], r0[8], r1[8];
;         const float ri0 = __builtin_amdgcn_rcpf(__builtin_amdgcn_exp2f(fmaxf(of0, -100.f))), ri1 = __builtin_amdgcn_rcpf(__builtin_amdgcn_exp2f(fmaxf(of1, -100.f)));
; #pragma unroll
;         for (int i = 0; i < 8; ++i) { const int j = 8 * tqs + i;
;             const float e0 = __builtin_amdgcn_exp2f(fmaxf(c0[i], -100.f)), e1 = __builtin_amdgcn_exp2f(fmaxf(c1[i], -100.f));
;             r0[i] = __builtin_amdgcn_rcpf(e0); r1[i] = __builtin_amdgcn_rcpf(e1);
;             if (seg) Qp[j * (HP / 2) + kp] = pk2(pg8::bflo(q_c[i]) * e0, pg8::bfhi(q_c[i]) * e1); }
; #pragma unroll
;         for (int i = 0; i < 8; ++i) { const int j = 8 * tqs + i;
;             const float p0 = dir ? (i < 7 ? r0[i < 7 ? i + 1 : 7] : ri0) : (i > 0 ? r0[i > 0 ? i - 1 : 0] : ri0), p1 = dir ? (i < 7 ? r1[i < 7 ? i + 1 : 7] : ri1) : (i > 0 ? r1[i > 0 ? i - 1 : 0] : ri1);
;             k0v[i] = r0[i] - p0; k1v[i] = r1[i] - p1;
;             Kt[j * (HP / 2) + kp] = pk2(k0v[i], k1v[i]); }
;         { u32x4 w; w.x = pk2(k0v[0], k0v[1]); w.y = pk2(k0v[2], k0v[3]); w.z = pk2(k0v[4], k0v[5]); w.w = pk2(k0v[6], k0v[7]); *(LAS u32x4*)(KtT + (2 * kp) * HKP + 8 * tqs) = w; }
;         { u32x4 w; w.x = pk2(k1v[0], k1v[1]); w.y = pk2(k1v[2], k1v[3]); w.z = pk2(k1v[4], k1v[5]); w.w = pk2(k1v[6], k1v[7]); *(LAS u32x4*)(KtT + (2 * kp + 1) * HKP + 8 * tqs) = w; }
;         if (tqs == 0) { dv[2 * kp] = d0; dv[2 * kp + 1] = d1; }
.LBB0_488:
	v_max_f32_e32 v28, 0xc2c80000, v28
	v_max_f32_e32 v29, 0xc2c80000, v50
	s_cmp_gt_u32 s50, 7
	s_mul_i32 s44, s44, 0x9000
	v_exp_f32_e32 v28, v28
	v_exp_f32_e32 v29, v29
	s_cselect_b64 s[38:39], -1, 0
	s_add_i32 s51, s44, 0
	v_lshl_add_u32 v50, v186, 2, s51
	s_cmp_lt_u32 s50, 8
	v_add_u32_e32 v76, s21, v50
	s_cbranch_scc1 .LBB0_490
	v_lshlrev_b32_e32 v66, 16, v44
	v_and_b32_e32 v67, 0xffff0000, v44
	v_pk_mul_f32 v[66:67], v[28:29], v[66:67]
	s_nop 0
	v_cvt_pk_bf16_f32 v44, v66, v67
	ds_write_b32 v76, v44 offset:8704
.LBB0_490:
	v_max_f32_e32 v30, 0xc2c80000, v30
	v_max_f32_e32 v31, 0xc2c80000, v31
	v_exp_f32_e32 v30, v30
	v_exp_f32_e32 v31, v31
	v_cndmask_b32_e64 v44, 0, 1, s[38:39]
	v_cmp_ne_u32_e64 s[36:37], 1, v44
	s_andn2_b64 vcc, exec, s[38:39]
	s_cbranch_vccnz .LBB0_492
	v_lshlrev_b32_e32 v44, 16, v45
	v_and_b32_e32 v45, 0xffff0000, v45
	v_pk_mul_f32 v[44:45], v[30:31], v[44:45]
	s_nop 0
	v_cvt_pk_bf16_f32 v44, v44, v45
	ds_write_b32 v76, v44 offset:8976
.LBB0_492:
	v_max_f32_e32 v32, 0xc2c80000, v32
	v_max_f32_e32 v33, 0xc2c80000, v33
	v_exp_f32_e32 v32, v32
	v_exp_f32_e32 v33, v33
	s_and_b64 vcc, exec, s[36:37]
	s_cbranch_vccnz .LBB0_494
	v_lshlrev_b32_e32 v44, 16, v46
	v_and_b32_e32 v45, 0xffff0000, v46
	v_pk_mul_f32 v[44:45], v[32:33], v[44:45]
	s_nop 0
	v_cvt_pk_bf16_f32 v44, v44, v45
	ds_write_b32 v76, v44 offset:9248
.LBB0_494:
	v_max_f32_e32 v34, 0xc2c80000, v34
	v_max_f32_e32 v35, 0xc2c80000, v35
	v_exp_f32_e32 v34, v34
	v_exp_f32_e32 v35, v35
	s_and_b64 vcc, exec, s[36:37]
	s_cbranch_vccnz .LBB0_496
	v_lshlrev_b32_e32 v44, 16, v47
	v_and_b32_e32 v45, 0xffff0000, v47
	v_pk_mul_f32 v[44:45], v[34:35], v[44:45]
	s_nop 0
	v_cvt_pk_bf16_f32 v44, v44, v45
	ds_write_b32 v76, v44 offset:9520
.LBB0_496:
	v_max_f32_e32 v36, 0xc2c80000, v36
	v_max_f32_e32 v37, 0xc2c80000, v37
	v_exp_f32_e32 v36, v36
	v_exp_f32_e32 v37, v37
	s_and_b64 vcc, exec, s[36:37]
	s_cbranch_vccnz .LBB0_498
	v_lshlrev_b32_e32 v44, 16, v48
	v_and_b32_e32 v45, 0xffff0000, v48
	v_pk_mul_f32 v[44:45], v[36:37], v[44:45]
	s_nop 0
	v_cvt_pk_bf16_f32 v44, v44, v45
	ds_write_b32 v76, v44 offset:9792
.LBB0_498:
	v_max_f32_e32 v38, 0xc2c80000, v38
	v_max_f32_e32 v39, 0xc2c80000, v39
	v_exp_f32_e32 v38, v38
	v_exp_f32_e32 v39, v39
	s_and_b64 vcc, exec, s[36:37]
	s_cbranch_vccnz .LBB0_500
	v_lshlrev_b32_e32 v44, 16, v49
	v_and_b32_e32 v45, 0xffff0000, v49
	v_pk_mul_f32 v[44:45], v[38:39], v[44:45]
	s_nop 0
	v_cvt_pk_bf16_f32 v44, v44, v45
	ds_write_b32 v76, v44 offset:10064
.LBB0_500:
	v_max_f32_e32 v40, 0xc2c80000, v40
	v_max_f32_e32 v41, 0xc2c80000, v41
	v_exp_f32_e32 v40, v40
	v_exp_f32_e32 v41, v41
	s_and_b64 vcc, exec, s[36:37]
	s_cbranch_vccnz .LBB0_502
	v_lshlrev_b32_e32 v44, 16, v51
	v_and_b32_e32 v45, 0xffff0000, v51
	v_pk_mul_f32 v[44:45], v[40:41], v[44:45]
	s_nop 0
	v_cvt_pk_bf16_f32 v44, v44, v45
	ds_write_b32 v76, v44 offset:10336
.LBB0_502:
	v_max_f32_e32 v42, 0xc2c80000, v42
	v_max_f32_e32 v43, 0xc2c80000, v43
	v_exp_f32_e32 v42, v42
	v_exp_f32_e32 v43, v43
	s_and_b64 vcc, exec, s[36:37]
	s_cbranch_vccnz .LBB0_504
	v_lshlrev_b32_e32 v44, 16, v56
	v_and_b32_e32 v45, 0xffff0000, v56
	v_pk_mul_f32 v[44:45], v[42:43], v[44:45]
	s_nop 0
	v_cvt_pk_bf16_f32 v44, v44, v45
	ds_write_b32 v76, v44 offset:10608
.LBB0_504:
	v_max_f32_e32 v44, 0xc2c80000, v78
	v_max_f32_e32 v45, 0xc2c80000, v79
	v_exp_f32_e32 v44, v44
	v_exp_f32_e32 v45, v45
	v_rcp_f32_e32 v30, v30
	v_rcp_f32_e32 v31, v31
	v_rcp_f32_e32 v44, v44
	v_rcp_f32_e32 v45, v45
	v_rcp_f32_e32 v32, v32
	v_rcp_f32_e32 v33, v33
	v_rcp_f32_e32 v28, v28
	v_rcp_f32_e32 v29, v29
	v_rcp_f32_e32 v34, v34
	v_rcp_f32_e32 v35, v35
	v_rcp_f32_e32 v36, v36
	v_rcp_f32_e32 v37, v37
	v_cndmask_b32_e64 v46, v30, v44, s[22:23]
	v_cndmask_b32_e64 v47, v31, v45, s[22:23]
	v_sub_f32_e32 v46, v28, v46
	v_sub_f32_e32 v47, v29, v47
	v_cndmask_b32_e64 v28, v32, v28, s[22:23]
	v_cndmask_b32_e64 v29, v33, v29, s[22:23]
	v_sub_f32_e32 v28, v30, v28
	v_sub_f32_e32 v29, v31, v29
	v_rcp_f32_e32 v39, v39
	v_cvt_pk_bf16_f32 v48, v46, v47
	v_cvt_pk_bf16_f32 v49, v28, v29
	v_add_u32_e32 v78, 0x4400, v76
	v_cndmask_b32_e64 v30, v34, v30, s[22:23]
	v_cndmask_b32_e64 v31, v35, v31, s[22:23]
	v_rcp_f32_e32 v40, v40
	v_rcp_f32_e32 v41, v41
	v_rcp_f32_e32 v38, v38
	ds_write2_b32 v78, v48, v49 offset1:68
	v_sub_f32_e32 v48, v32, v30
	v_sub_f32_e32 v49, v33, v31
	v_cndmask_b32_e64 v31, v36, v32, s[22:23]
	v_cndmask_b32_e64 v32, v37, v33, s[22:23]
	v_sub_f32_e32 v31, v34, v31
	v_sub_f32_e32 v50, v35, v32
	v_cvt_pk_bf16_f32 v30, v48, v49
	v_cvt_pk_bf16_f32 v32, v31, v50
	v_rcp_f32_e32 v42, v42
	v_rcp_f32_e32 v43, v43
	ds_write2_b32 v78, v30, v32 offset0:136 offset1:204
	v_cndmask_b32_e64 v32, v39, v35, s[22:23]
	v_cndmask_b32_e64 v30, v38, v34, s[22:23]
	v_sub_f32_e32 v34, v37, v32
	v_cndmask_b32_e64 v32, v40, v36, s[22:23]
	v_cndmask_b32_e64 v35, v41, v37, s[22:23]
	v_sub_f32_e32 v33, v36, v30
	v_sub_f32_e32 v32, v38, v32
	v_sub_f32_e32 v35, v39, v35
	v_cvt_pk_bf16_f32 v30, v33, v34
	v_cvt_pk_bf16_f32 v36, v32, v35
	v_add_u32_e32 v79, 0x4800, v76
	ds_write2_b32 v79, v30, v36 offset0:16 offset1:84
	v_cndmask_b32_e64 v30, v42, v38, s[22:23]
	v_cndmask_b32_e64 v36, v43, v39, s[22:23]
	v_cndmask_b32_e64 v38, v44, v40, s[22:23]
	v_cndmask_b32_e64 v39, v45, v41, s[22:23]
	v_sub_f32_e32 v37, v40, v30
	v_sub_f32_e32 v36, v41, v36
	v_sub_f32_e32 v38, v42, v38
	v_sub_f32_e32 v39, v43, v39
	v_cvt_pk_bf16_f32 v30, v37, v36
	v_cvt_pk_bf16_f32 v40, v38, v39
	ds_write2_b32 v79, v30, v40 offset0:152 offset1:220
	v_cvt_pk_bf16_f32 v30, v46, v28
	v_add_u32_e32 v28, s51, v203
	s_lshl_b32 s53, s20, 1
	v_cvt_pk_bf16_f32 v31, v48, v31
	v_cvt_pk_bf16_f32 v32, v33, v32
	v_cvt_pk_bf16_f32 v33, v37, v38
	v_add_u32_e32 v80, s53, v28
	ds_write_b128 v80, v[30:33] offset:26112
	v_cvt_pk_bf16_f32 v30, v47, v29
	s_add_i32 s36, s53, s51
	v_cndmask_b32_e64 v29, 0, 1, s[24:25]
	v_cvt_pk_bf16_f32 v31, v49, v50
	v_cvt_pk_bf16_f32 v32, v34, v35
	v_cvt_pk_bf16_f32 v33, v36, v39
	v_add_u32_e32 v81, s36, v204
	v_cmp_ne_u32_e64 s[36:37], 1, v29
	s_andn2_b64 vcc, exec, s[24:25]
	ds_write_b128 v81, v[30:33] offset:26112
	s_cbranch_vccnz .LBB0_506
	s_waitcnt lgkmcnt(7)
	v_pk_add_f32 v[2:3], v[2:3], v[4:5]
	s_waitcnt lgkmcnt(6)
	v_pk_add_f32 v[4:5], v[6:7], v[8:9]
	s_nop 0
	v_pk_add_f32 v[2:3], v[2:3], v[4:5]
	v_add_u32_e32 v4, v28, v208
	v_exp_f32_e32 v2, v2
	v_exp_f32_e32 v3, v3
	ds_write_b64 v4, v[2:3] offset:36352

; __device__ __forceinline__ float bflo(unsigned u) { return __uint_as_float(u << 16); }
; __device__ __forceinline__ float bfhi(unsigned u) { return __uint_as_float(u & 0xffff0000u); }
; #define LAS __attribute__((address_space(3)))
; DI unsigned pk2(float lo, float hi) { f32x2_t v = {lo, hi}; bf16x2_t b = __builtin_convertvector(v, bf16x2_t); return __builtin_bit_cast(unsigned, b); }
; template <int NC> DI void hg_gate_tick(const HgGate& c, int t, const unsigned (&xo_c)[8], const unsigned (&q_c)[8], const unsigned (&xo_n)[8], unsigned (&xo_p)[8], unsigned (&q_p)[8]) {
;     ...
;         const float d0 = __builtin_amdgcn_exp2f(tot0), d1 = __builtin_amdgcn_exp2f(tot1);
;         float k0v[8], k1v[8], r0[8], r1[8];
;         const float ri0 = __builtin_amdgcn_rcpf(__builtin_amdgcn_exp2f(fmaxf(of0, -100.f))), ri1 = __builtin_amdgcn_rcpf(__builtin_amdgcn_exp2f(fmaxf(of1, -100.f)));
; #pragma unroll
;         for (int i = 0; i < 8; ++i) { const int j = 8 * tqs + i;
;             const float e0 = __builtin_amdgcn_exp2f(fmaxf(c0[i], -100.f)), e1 = __builtin_amdgcn_exp2f(fmaxf(c1[i], -100.f));
;             r0[i] = __builtin_amdgcn_rcpf(e0); r1[i] = __builtin_amdgcn_rcpf(e1);
;             if (seg) Qp[j * (HP / 2) + kp] = pk2(pg8::bflo(q_c[i]) * e0, pg8::bfhi(q_c[i]) * e1); }
; #pragma unroll
;         for (int i = 0; i < 8; ++i) { const int j = 8 * tqs + i;
;             const float p0 = dir ? (i < 7 ? r0[i < 7 ? i + 1 : 7] : ri0) : (i > 0 ? r0[i > 0 ? i - 1 : 0] : ri0), p1 = dir ? (i < 7 ? r1[i < 7 ? i + 1 : 7] : ri1) : (i > 0 ? r1[i > 0 ? i - 1 : 0] : ri1);
;             k0v[i] = r0[i] - p0; k1v[i] = r1[i] - p1;
;             Kt[j * (HP / 2) + kp] = pk2(k0v[i], k1v[i]); }
;         { u32x4 w; w.x = pk2(k0v[0], k0v[1]); w.y = pk2(k0v[2], k0v[3]); w.z = pk2(k0v[4], k0v[5]); w.w = pk2(k0v[6], k0v[7]); *(LAS u32x4*)(KtT + (2 * kp) * HKP + 8 * tqs) = w; }
;         { u32x4 w; w.x = pk2(k1v[0], k1v[1]); w.y = pk2(k1v[2], k1v[3]); w.z = pk2(k1v[4], k1v[5]); w.w = pk2(k1v[6], k1v[7]); *(LAS u32x4*)(KtT + (2 * kp + 1) * HKP + 8 * tqs) = w; }
;         if (tqs == 0) { dv[2 * kp] = d0; dv[2 * kp + 1] = d1; }
.LBB0_522:
	v_max_f32_e32 v12, 0xc2c80000, v90
	v_max_f32_e32 v13, 0xc2c80000, v99
	s_cmp_gt_u32 s50, 6
	s_mul_i32 s46, s46, 0x9000
	v_exp_f32_e32 v12, v12
	v_exp_f32_e32 v13, v13
	s_cselect_b64 s[44:45], -1, 0
	s_add_i32 s46, s46, 0
	v_lshl_add_u32 v14, v186, 2, s46
	s_cmp_lt_u32 s50, 7
	v_add_u32_e32 v90, s21, v14
	s_cbranch_scc1 .LBB0_524
	v_lshlrev_b32_e32 v14, 16, v52
	v_and_b32_e32 v15, 0xffff0000, v52
	v_pk_mul_f32 v[14:15], v[12:13], v[14:15]
	s_nop 0
	v_cvt_pk_bf16_f32 v14, v14, v15
	ds_write_b32 v90, v14 offset:8704
.LBB0_524:
	v_max_f32_e32 v14, 0xc2c80000, v97
	v_max_f32_e32 v15, 0xc2c80000, v98
	v_exp_f32_e32 v14, v14
	v_exp_f32_e32 v15, v15
	v_cndmask_b32_e64 v16, 0, 1, s[44:45]
	v_cmp_ne_u32_e64 s[38:39], 1, v16
	s_andn2_b64 vcc, exec, s[44:45]
	s_cbranch_vccnz .LBB0_526
	v_lshlrev_b32_e32 v16, 16, v54
	v_and_b32_e32 v17, 0xffff0000, v54
	v_pk_mul_f32 v[16:17], v[14:15], v[16:17]
	s_nop 0
	v_cvt_pk_bf16_f32 v16, v16, v17
	ds_write_b32 v90, v16 offset:8976
.LBB0_526:
	v_max_f32_e32 v16, 0xc2c80000, v95
	v_max_f32_e32 v17, 0xc2c80000, v96
	v_exp_f32_e32 v16, v16
	v_exp_f32_e32 v17, v17
	s_and_b64 vcc, exec, s[38:39]
	s_cbranch_vccnz .LBB0_528
	v_lshlrev_b32_e32 v18, 16, v55
	v_and_b32_e32 v19, 0xffff0000, v55
	v_pk_mul_f32 v[18:19], v[16:17], v[18:19]
	s_nop 0
	v_cvt_pk_bf16_f32 v18, v18, v19
	ds_write_b32 v90, v18 offset:9248
.LBB0_528:
	v_max_f32_e32 v18, 0xc2c80000, v93
	v_max_f32_e32 v19, 0xc2c80000, v94
	v_exp_f32_e32 v18, v18
	v_exp_f32_e32 v19, v19
	s_and_b64 vcc, exec, s[38:39]
	s_cbranch_vccnz .LBB0_530
	v_lshlrev_b32_e32 v20, 16, v58
	v_and_b32_e32 v21, 0xffff0000, v58
	v_pk_mul_f32 v[20:21], v[18:19], v[20:21]
	s_nop 0
	v_cvt_pk_bf16_f32 v20, v20, v21
	ds_write_b32 v90, v20 offset:9520
.LBB0_530:
	v_max_f32_e32 v20, 0xc2c80000, v91
	v_max_f32_e32 v21, 0xc2c80000, v92
	v_exp_f32_e32 v20, v20
	v_exp_f32_e32 v21, v21
	s_and_b64 vcc, exec, s[38:39]
	s_cbranch_vccnz .LBB0_532
	v_lshlrev_b32_e32 v22, 16, v60
	v_and_b32_e32 v23, 0xffff0000, v60
	v_pk_mul_f32 v[22:23], v[20:21], v[22:23]
	s_nop 0
	v_cvt_pk_bf16_f32 v22, v22, v23
	ds_write_b32 v90, v22 offset:9792
.LBB0_532:
	v_max_f32_e32 v22, 0xc2c80000, v88
	v_max_f32_e32 v23, 0xc2c80000, v89
	v_exp_f32_e32 v22, v22
	v_exp_f32_e32 v23, v23
	s_and_b64 vcc, exec, s[38:39]
	s_cbranch_vccnz .LBB0_534
	v_lshlrev_b32_e32 v24, 16, v61
	v_and_b32_e32 v25, 0xffff0000, v61
	v_pk_mul_f32 v[24:25], v[22:23], v[24:25]
	s_nop 0
	v_cvt_pk_bf16_f32 v24, v24, v25
	ds_write_b32 v90, v24 offset:10064
.LBB0_534:
	v_max_f32_e32 v24, 0xc2c80000, v86
	v_max_f32_e32 v25, 0xc2c80000, v87
	v_exp_f32_e32 v24, v24
	v_exp_f32_e32 v25, v25
	s_and_b64 vcc, exec, s[38:39]
	s_cbranch_vccnz .LBB0_536
	v_lshlrev_b32_e32 v26, 16, v62
	v_and_b32_e32 v27, 0xffff0000, v62
	v_pk_mul_f32 v[26:27], v[24:25], v[26:27]
	s_nop 0
	v_cvt_pk_bf16_f32 v26, v26, v27
	ds_write_b32 v90, v26 offset:10336
.LBB0_536:
	v_max_f32_e32 v26, 0xc2c80000, v84
	v_max_f32_e32 v27, 0xc2c80000, v85
	v_exp_f32_e32 v26, v26
	v_exp_f32_e32 v27, v27
	s_and_b64 vcc, exec, s[38:39]
	s_cbranch_vccnz .LBB0_538
	v_lshlrev_b32_e32 v54, 16, v65
	v_and_b32_e32 v55, 0xffff0000, v65
	v_pk_mul_f32 v[54:55], v[26:27], v[54:55]
	s_nop 0
	v_cvt_pk_bf16_f32 v52, v54, v55
	ds_write_b32 v90, v52 offset:10608
.LBB0_538:
	v_max_f32_e32 v52, 0xc2c80000, v82
	v_max_f32_e32 v54, 0xc2c80000, v83
	v_exp_f32_e32 v52, v52
	v_exp_f32_e32 v54, v54
	v_rcp_f32_e32 v14, v14
	v_rcp_f32_e32 v15, v15
	v_rcp_f32_e32 v52, v52
	v_rcp_f32_e32 v54, v54
	v_rcp_f32_e32 v16, v16
	v_rcp_f32_e32 v17, v17
	v_rcp_f32_e32 v12, v12
	v_rcp_f32_e32 v13, v13
	v_rcp_f32_e32 v18, v18
	v_rcp_f32_e32 v19, v19
	v_rcp_f32_e32 v20, v20
	v_rcp_f32_e32 v21, v21
	v_cndmask_b32_e64 v55, v14, v52, s[22:23]
	v_cndmask_b32_e64 v58, v15, v54, s[22:23]
	v_sub_f32_e32 v55, v12, v55
	v_sub_f32_e32 v58, v13, v58
	v_cndmask_b32_e64 v12, v16, v12, s[22:23]
	v_cndmask_b32_e64 v13, v17, v13, s[22:23]
	v_sub_f32_e32 v12, v14, v12
	v_sub_f32_e32 v13, v15, v13
	v_rcp_f32_e32 v23, v23
	v_cvt_pk_bf16_f32 v60, v55, v58
	v_cvt_pk_bf16_f32 v61, v12, v13
	v_add_u32_e32 v62, 0x4400, v90
	v_cndmask_b32_e64 v14, v18, v14, s[22:23]
	v_cndmask_b32_e64 v15, v19, v15, s[22:23]
	v_rcp_f32_e32 v24, v24
	v_rcp_f32_e32 v25, v25
	v_rcp_f32_e32 v22, v22
	ds_write2_b32 v62, v60, v61 offset1:68
	v_sub_f32_e32 v60, v16, v14
	v_sub_f32_e32 v61, v17, v15
	v_cndmask_b32_e64 v15, v20, v16, s[22:23]
	v_cndmask_b32_e64 v16, v21, v17, s[22:23]
	v_sub_f32_e32 v15, v18, v15
	v_sub_f32_e32 v65, v19, v16
	v_cvt_pk_bf16_f32 v14, v60, v61
	v_cvt_pk_bf16_f32 v16, v15, v65
	v_rcp_f32_e32 v26, v26
	ds_write2_b32 v62, v14, v16 offset0:136 offset1:204
	v_cndmask_b32_e64 v16, v23, v19, s[22:23]
	v_rcp_f32_e32 v27, v27
	v_cndmask_b32_e64 v14, v22, v18, s[22:23]
	v_sub_f32_e32 v18, v21, v16
	v_cndmask_b32_e64 v16, v24, v20, s[22:23]
	v_cndmask_b32_e64 v19, v25, v21, s[22:23]
	v_sub_f32_e32 v17, v20, v14
	v_sub_f32_e32 v16, v22, v16
	v_sub_f32_e32 v19, v23, v19
	v_cvt_pk_bf16_f32 v14, v17, v18
	v_cvt_pk_bf16_f32 v20, v16, v19
	v_add_u32_e32 v21, 0x4800, v90
	ds_write2_b32 v21, v14, v20 offset0:16 offset1:84
	v_cndmask_b32_e64 v14, v26, v22, s[22:23]
	v_cndmask_b32_e64 v20, v27, v23, s[22:23]
	v_sub_f32_e32 v22, v24, v14
	v_cndmask_b32_e64 v23, v52, v24, s[22:23]
	v_cndmask_b32_e64 v24, v54, v25, s[22:23]
	v_sub_f32_e32 v20, v25, v20
	v_sub_f32_e32 v23, v26, v23
	v_sub_f32_e32 v24, v27, v24
	v_cvt_pk_bf16_f32 v14, v22, v20
	v_cvt_pk_bf16_f32 v25, v23, v24
	ds_write2_b32 v21, v14, v25 offset0:152 offset1:220
	v_cvt_pk_bf16_f32 v14, v55, v12
	v_add_u32_e32 v12, s46, v203
	v_cvt_pk_bf16_f32 v15, v60, v15
	v_cvt_pk_bf16_f32 v16, v17, v16
	v_cvt_pk_bf16_f32 v17, v22, v23
	v_add_u32_e32 v21, s53, v12
	s_add_i32 s53, s53, s46
	ds_write_b128 v21, v[14:17] offset:26112
	v_cvt_pk_bf16_f32 v14, v58, v13
	v_cvt_pk_bf16_f32 v15, v61, v65
	v_cvt_pk_bf16_f32 v16, v18, v19
	v_cvt_pk_bf16_f32 v17, v20, v24
	v_add_u32_e32 v13, s53, v204
	s_and_b64 vcc, exec, s[36:37]
	ds_write_b128 v13, v[14:17] offset:26112
	s_cbranch_vccnz .LBB0_540
	s_waitcnt lgkmcnt(7)
	v_pk_add_f32 v[2:3], v[2:3], v[4:5]
	s_waitcnt lgkmcnt(6)
	v_pk_add_f32 v[4:5], v[6:7], v[8:9]
	s_nop 0
	v_pk_add_f32 v[2:3], v[2:3], v[4:5]
	v_add_u32_e32 v4, v12, v208
	v_exp_f32_e32 v2, v2
	v_exp_f32_e32 v3, v3
	ds_write_b64 v4, v[2:3] offset:36352

; __device__ __forceinline__ float bflo(unsigned u) { return __uint_as_float(u << 16); }
; __device__ __forceinline__ float bfhi(unsigned u) { return __uint_as_float(u & 0xffff0000u); }
; DI unsigned pk2(float lo, float hi) { f32x2_t v = {lo, hi}; bf16x2_t b = __builtin_convertvector(v, bf16x2_t); return __builtin_bit_cast(unsigned, b); }
; template <int NC> DI void hg_gate_tick(const HgGate& c, int t, const unsigned (&xo_c)[8], const unsigned (&q_c)[8], const unsigned (&xo_n)[8], unsigned (&xo_p)[8], unsigned (&q_p)[8]) {
;     ...
;         for (int i = 0; i < 8; ++i) { const int j = 8 * tqs + i;
;             const float e0 = __builtin_amdgcn_exp2f(fmaxf(c0[i], -100.f)), e1 = __builtin_amdgcn_exp2f(fmaxf(c1[i], -100.f));
;             r0[i] = __builtin_amdgcn_rcpf(e0); r1[i] = __builtin_amdgcn_rcpf(e1);
;             if (seg) Qp[j * (HP / 2) + kp] = pk2(pg8::bflo(q_c[i]) * e0, pg8::bfhi(q_c[i]) * e1); }
.LBB0_556:
	v_max_f32_e32 v12, 0xc2c80000, v12
	v_max_f32_e32 v13, 0xc2c80000, v13
	v_exp_f32_e32 v12, v12
	v_exp_f32_e32 v13, v13
	v_cndmask_b32_e64 v28, 0, 1, s[8:9]
	v_cmp_ne_u32_e64 s[34:35], 1, v28
	s_andn2_b64 vcc, exec, s[8:9]
	s_cbranch_vccnz .LBB0_558
	v_lshlrev_b32_e32 v28, 16, v68
	v_and_b32_e32 v29, 0xffff0000, v68
	v_pk_mul_f32 v[28:29], v[12:13], v[28:29]
	s_nop 0
	v_cvt_pk_bf16_f32 v28, v28, v29
	ds_write_b32 v76, v28 offset:8704
.LBB0_558:
	v_max_f32_e32 v14, 0xc2c80000, v14
	v_max_f32_e32 v15, 0xc2c80000, v15
	v_exp_f32_e32 v14, v14
	v_exp_f32_e32 v15, v15
	s_and_b64 vcc, exec, s[34:35]
	s_cbranch_vccnz .LBB0_560
	v_lshlrev_b32_e32 v28, 16, v69
	v_and_b32_e32 v29, 0xffff0000, v69
	v_pk_mul_f32 v[28:29], v[14:15], v[28:29]
	s_nop 0
	v_cvt_pk_bf16_f32 v28, v28, v29
	ds_write_b32 v76, v28 offset:8976
.LBB0_560:
	v_max_f32_e32 v16, 0xc2c80000, v16
	v_max_f32_e32 v17, 0xc2c80000, v17
	v_exp_f32_e32 v16, v16
	v_exp_f32_e32 v17, v17
	s_and_b64 vcc, exec, s[34:35]
	s_cbranch_vccnz .LBB0_562
	v_lshlrev_b32_e32 v28, 16, v70
	v_and_b32_e32 v29, 0xffff0000, v70
	v_pk_mul_f32 v[28:29], v[16:17], v[28:29]
	s_nop 0
	v_cvt_pk_bf16_f32 v28, v28, v29
	ds_write_b32 v76, v28 offset:9248
.LBB0_562:
	v_max_f32_e32 v18, 0xc2c80000, v18
	v_max_f32_e32 v19, 0xc2c80000, v19
	v_exp_f32_e32 v18, v18
	v_exp_f32_e32 v19, v19
	s_and_b64 vcc, exec, s[34:35]
	s_cbranch_vccnz .LBB0_564
	v_lshlrev_b32_e32 v28, 16, v71
	v_and_b32_e32 v29, 0xffff0000, v71
	v_pk_mul_f32 v[28:29], v[18:19], v[28:29]
	s_nop 0
	v_cvt_pk_bf16_f32 v28, v28, v29
	ds_write_b32 v76, v28 offset:9520
.LBB0_564:
	v_max_f32_e32 v20, 0xc2c80000, v20
	v_max_f32_e32 v21, 0xc2c80000, v21
	v_exp_f32_e32 v20, v20
	v_exp_f32_e32 v21, v21
	s_and_b64 vcc, exec, s[34:35]
	s_cbranch_vccnz .LBB0_566
	v_lshlrev_b32_e32 v28, 16, v72
	v_and_b32_e32 v29, 0xffff0000, v72
	v_pk_mul_f32 v[28:29], v[20:21], v[28:29]
	s_nop 0
	v_cvt_pk_bf16_f32 v28, v28, v29
	ds_write_b32 v76, v28 offset:9792
.LBB0_566:
	v_max_f32_e32 v22, 0xc2c80000, v22
	v_max_f32_e32 v23, 0xc2c80000, v23
	v_exp_f32_e32 v22, v22
	v_exp_f32_e32 v23, v23
	s_and_b64 vcc, exec, s[34:35]
	s_cbranch_vccnz .LBB0_568
	v_lshlrev_b32_e32 v28, 16, v73
	v_and_b32_e32 v29, 0xffff0000, v73
	v_pk_mul_f32 v[28:29], v[22:23], v[28:29]
	s_nop 0
	v_cvt_pk_bf16_f32 v28, v28, v29
	ds_write_b32 v76, v28 offset:10064
.LBB0_568:
	v_max_f32_e32 v24, 0xc2c80000, v24
	v_max_f32_e32 v25, 0xc2c80000, v25
	v_exp_f32_e32 v24, v24
	v_exp_f32_e32 v25, v25
	s_and_b64 vcc, exec, s[34:35]
	s_cbranch_vccnz .LBB0_570
	v_lshlrev_b32_e32 v28, 16, v74
	v_and_b32_e32 v29, 0xffff0000, v74
	v_pk_mul_f32 v[28:29], v[24:25], v[28:29]
	s_nop 0
	v_cvt_pk_bf16_f32 v28, v28, v29
	ds_write_b32 v76, v28 offset:10336
.LBB0_570:
	v_max_f32_e32 v26, 0xc2c80000, v26
	v_max_f32_e32 v27, 0xc2c80000, v27
	v_exp_f32_e32 v26, v26
	v_exp_f32_e32 v27, v27
	s_and_b64 vcc, exec, s[34:35]
	s_cbranch_vccnz .LBB0_472
	v_lshlrev_b32_e32 v28, 16, v75
	v_and_b32_e32 v29, 0xffff0000, v75
	v_pk_mul_f32 v[28:29], v[26:27], v[28:29]
	s_nop 0
	v_cvt_pk_bf16_f32 v28, v28, v29
	ds_write_b32 v76, v28 offset:10608
	s_branch .LBB0_472
